# v28 + NSA loops: post-QK hazard wait states filled with the P.V address arithmetic and the first four transposed V reads
# speedup vs baseline: 1.0069x; 1.0069x over previous
; __device__ __forceinline__ s16x4 vtr(lds_cptr p){ return __builtin_bit_cast(s16x4,__builtin_amdgcn_ds_read_tr16_b64_v4i16((__attribute__((address_space(3))) v4i16_t*)p)); }
; #define LAS __attribute__((address_space(3)))
; __device__ __forceinline__ s16x4 vtr(LAS const unsigned char* p) { return __builtin_bit_cast(s16x4, __builtin_amdgcn_ds_read_tr16_b64_v4i16((LAS v4i16_t*)p)); }
; __device__ __forceinline__ void pv_tile(f32x16& o0, f32x16& o1, LAS const unsigned char* Vt, const bf16x8 (&pf)[4], int lane) {
;     const int q = (lane & 15) >> 2, swz = ((q >> 1) & 1) * 64;
;     LAS const unsigned char* vp0 = Vt + (4 * (lane >> 5) + q) * 128 + (((16 * ((lane >> 4) & 1) + 4 * (lane & 3)) * 2) ^ swz);
;     LAS const unsigned char* vp1 = Vt + (4 * (lane >> 5) + q) * 128 + (((16 * ((lane >> 4) & 1) + 4 * (lane & 3)) * 2 + 64) ^ swz);
; #pragma unroll
;     for (int s = 0; s < 4; ++s) {
;         const s16x4 l0 = vtr(vp0 + (16 * s) * 128), h0 = vtr(vp0 + (16 * s + 8) * 128), l1 = vtr(vp1 + (16 * s) * 128), h1 = vtr(vp1 + (16 * s + 8) * 128);
.LBB0_965:
	v_add_u32_e32 v10, s50, v188
	v_add3_u32 v114, v10, v181, v180
	v_add_u32_e32 v115, v10, v182
	ds_read_b64_tr_b16 v[6:7], v114 offset:8192
	ds_read_b64_tr_b16 v[8:9], v114 offset:9216
	ds_read_b64_tr_b16 v[10:11], v115 offset:8192
	ds_read_b64_tr_b16 v[12:13], v115 offset:9216
	s_nop 2
	v_max_f32_e32 v2, v97, v97
	v_max_f32_e32 v3, v96, v96
	v_max_f32_e32 v2, v3, v2
	v_max3_f32 v3, v98, v99, v81
	v_max3_f32 v2, v2, v80, v82
	v_max3_f32 v2, v2, v83, v100
	v_max3_f32 v3, v3, v102, v103
	v_max3_f32 v2, v2, v101, v84
	v_max3_f32 v3, v3, v86, v87
	v_max3_f32 v2, v2, v85, v104
	v_max3_f32 v3, v3, v106, v107
	v_max3_f32 v2, v2, v105, v88
	v_max3_f32 v3, v3, v90, v91
	v_max3_f32 v2, v2, v89, v108
	v_max3_f32 v3, v3, v110, v111
	v_max3_f32 v2, v2, v109, v92
	v_max3_f32 v3, v3, v94, v95
	v_max3_f32 v2, v2, v93, v3
	v_mov_b32_e32 v3, v2
	s_nop 1
	v_permlane32_swap_b32_e32 v2, v3
	s_xor_b64 s[6:7], s[62:63], -1
	v_max_f32_e32 v3, v3, v3
	v_max_f32_e32 v2, v2, v2
	v_max_f32_e32 v2, v2, v3
	v_cndmask_b32_e64 v3, 0, 1, s[6:7]
	v_cmp_ne_u32_e64 s[4:5], 1, v3
	s_andn2_b64 vcc, exec, s[6:7]
	s_mov_b64 s[6:7], -1
	s_cbranch_vccnz .LBB0_968
	v_cmp_lt_f32_e32 vcc, s91, v2
	s_cbranch_vccz .LBB0_974
	s_nop 0
	v_cndmask_b32_e32 v2, 0, v2, vcc

; __device__ __forceinline__ s16x4 vtr(lds_cptr p){ return __builtin_bit_cast(s16x4,__builtin_amdgcn_ds_read_tr16_b64_v4i16((__attribute__((address_space(3))) v4i16_t*)p)); }
; #define LAS __attribute__((address_space(3)))
; #define MFMA32(a, b, c) __builtin_amdgcn_mfma_f32_32x32x16_bf16((a), (b), (c), 0, 0, 0)
; __device__ __forceinline__ s16x4 vtr(LAS const unsigned char* p) { return __builtin_bit_cast(s16x4, __builtin_amdgcn_ds_read_tr16_b64_v4i16((LAS v4i16_t*)p)); }
; #define NL_WAITBAR(n) do { asm volatile("s_waitcnt vmcnt(" #n ") lgkmcnt(0)" ::: "memory"); __builtin_amdgcn_s_barrier(); asm volatile("" ::: "memory"); } while (0)
; __device__ __forceinline__ void pv_tile(f32x16& o0, f32x16& o1, LAS const unsigned char* Vt, const bf16x8 (&pf)[4], int lane) {
;     const int q = (lane & 15) >> 2, swz = ((q >> 1) & 1) * 64;
;     LAS const unsigned char* vp0 = Vt + (4 * (lane >> 5) + q) * 128 + (((16 * ((lane >> 4) & 1) + 4 * (lane & 3)) * 2) ^ swz);
;     LAS const unsigned char* vp1 = Vt + (4 * (lane >> 5) + q) * 128 + (((16 * ((lane >> 4) & 1) + 4 * (lane & 3)) * 2 + 64) ^ swz);
; #pragma unroll
;     for (int s = 0; s < 4; ++s) {
;         const s16x4 l0 = vtr(vp0 + (16 * s) * 128), h0 = vtr(vp0 + (16 * s + 8) * 128), l1 = vtr(vp1 + (16 * s) * 128), h1 = vtr(vp1 + (16 * s + 8) * 128);
;         const bf16x8 v0 = {l0[0], l0[1], l0[2], l0[3], h0[0], h0[1], h0[2], h0[3]}, v1 = {l1[0], l1[1], l1[2], l1[3], h1[0], h1[1], h1[2], h1[3]};
;         o0 = MFMA32(v0, pf[s], o0); o1 = MFMA32(v1, pf[s], o1); }
; __device__ __forceinline__ void nsa_unit(int b, int g, int tq, const Args& a, LAS unsigned char* lds, int tid, int wave, int lane, int& nxt) {
;     ...
;                 NL_WAITBAR(2);
.LBB0_972:
	v_exp_f32_e32 v14, v96
	v_exp_f32_e32 v15, v97
	v_exp_f32_e32 v98, v98
	v_exp_f32_e32 v99, v99
	v_exp_f32_e32 v100, v100
	v_exp_f32_e32 v101, v101
	v_exp_f32_e32 v102, v102
	v_exp_f32_e32 v103, v103
	v_exp_f32_e32 v96, v80
	v_exp_f32_e32 v97, v81
	v_exp_f32_e32 v112, v82
	v_exp_f32_e32 v113, v83
	ds_read_b64_tr_b16 v[80:81], v114 offset:10240
	ds_read_b64_tr_b16 v[82:83], v114 offset:11264
	v_cvt_pk_bf16_f32 v2, v14, v15
	v_cvt_pk_bf16_f32 v3, v98, v99
	v_cvt_pk_bf16_f32 v4, v100, v101
	v_cvt_pk_bf16_f32 v5, v102, v103
	v_exp_f32_e32 v104, v104
	v_exp_f32_e32 v105, v105
	s_waitcnt lgkmcnt(4)
	v_mfma_f32_32x32x16_bf16 v[48:63], v[6:9], v[2:5], v[48:63]
	v_exp_f32_e32 v106, v106
	v_exp_f32_e32 v107, v107
	v_exp_f32_e32 v108, v108
	v_exp_f32_e32 v109, v109
	ds_read_b64_tr_b16 v[6:7], v115 offset:10240
	ds_read_b64_tr_b16 v[8:9], v115 offset:11264
	v_exp_f32_e32 v110, v110
	v_exp_f32_e32 v111, v111
	s_waitcnt lgkmcnt(4)
	v_mfma_f32_32x32x16_bf16 v[64:79], v[10:13], v[2:5], v[64:79]
	v_cvt_pk_bf16_f32 v2, v104, v105
	v_cvt_pk_bf16_f32 v3, v106, v107
	v_cvt_pk_bf16_f32 v4, v108, v109
	v_cvt_pk_bf16_f32 v5, v110, v111
	v_exp_f32_e32 v84, v84
	v_exp_f32_e32 v85, v85
	v_exp_f32_e32 v86, v86
	s_waitcnt lgkmcnt(2)
	v_mfma_f32_32x32x16_bf16 v[48:63], v[80:83], v[2:5], v[48:63]
	v_exp_f32_e32 v87, v87
	ds_read_b64_tr_b16 v[80:81], v114 offset:12288
	ds_read_b64_tr_b16 v[82:83], v114 offset:13312
	v_cvt_pk_bf16_f32 v10, v96, v97
	v_cvt_pk_bf16_f32 v11, v112, v113
	v_cvt_pk_bf16_f32 v12, v84, v85
	v_cvt_pk_bf16_f32 v13, v86, v87
	v_exp_f32_e32 v92, v92
	s_waitcnt lgkmcnt(2)
	v_mfma_f32_32x32x16_bf16 v[64:79], v[6:9], v[2:5], v[64:79]
	ds_read_b64_tr_b16 v[2:3], v115 offset:12288
	ds_read_b64_tr_b16 v[4:5], v115 offset:13312
	ds_read_b64_tr_b16 v[6:7], v114 offset:14336
	ds_read_b64_tr_b16 v[8:9], v114 offset:15360
	v_exp_f32_e32 v93, v93
	v_exp_f32_e32 v88, v88
	v_exp_f32_e32 v89, v89
	v_exp_f32_e32 v90, v90
	v_exp_f32_e32 v91, v91
	v_exp_f32_e32 v94, v94
	s_waitcnt lgkmcnt(4)
	v_mfma_f32_32x32x16_bf16 v[48:63], v[80:83], v[10:13], v[48:63]
	v_exp_f32_e32 v95, v95
	ds_read_b64_tr_b16 v[80:81], v115 offset:14336
	ds_read_b64_tr_b16 v[82:83], v115 offset:15360
	v_add_f32_e32 v14, v96, v14
	v_add_f32_e32 v15, v97, v15
	v_add_f32_e32 v96, v92, v108
	v_add_f32_e32 v97, v93, v109
	v_add_f32_e32 v106, v90, v106
	v_add_f32_e32 v107, v91, v107
	v_add_f32_e32 v98, v112, v98
	v_add_f32_e32 v99, v113, v99
	v_add_f32_e32 v110, v94, v110
	v_add_f32_e32 v111, v95, v111
	s_waitcnt lgkmcnt(4)
	v_mfma_f32_32x32x16_bf16 v[64:79], v[2:5], v[10:13], v[64:79]
	v_add_f32_e64 v2, v84, v100
	v_add_f32_e64 v3, v85, v101
	v_cvt_pk_bf16_f32 v4, v92, v93
	v_add_f32_e64 v10, v2, v96
	v_add_f32_e64 v11, v3, v97
	v_cvt_pk_bf16_f32 v2, v88, v89
	v_cvt_pk_bf16_f32 v3, v90, v91
	v_cvt_pk_bf16_f32 v5, v94, v95
	v_add_f32_e32 v86, v86, v102
	v_add_f32_e32 v87, v87, v103
	v_add_f32_e32 v102, v88, v104
	v_add_f32_e32 v103, v89, v105
	s_waitcnt lgkmcnt(2)
	v_mfma_f32_32x32x16_bf16 v[48:63], v[6:9], v[2:5], v[48:63]
	v_add_f32_e64 v12, v14, v102
	v_add_f32_e64 v13, v15, v103
	v_add_f32_e64 v6, v86, v110
	v_add_f32_e64 v7, v87, v111
	v_add_f32_e64 v8, v98, v106
	v_add_f32_e64 v9, v99, v107
	s_waitcnt vmcnt(2) lgkmcnt(0)
	s_barrier
	v_add_f32_e32 v6, v8, v6
	v_add_f32_e32 v7, v9, v7
	v_add_f32_e32 v8, v12, v10
	v_add_f32_e32 v9, v13, v11
	s_waitcnt lgkmcnt(0)
	v_mfma_f32_32x32x16_bf16 v[64:79], v[80:83], v[2:5], v[64:79]
	v_add_f32_e64 v6, v8, v6
	v_add_f32_e64 v7, v9, v7
	s_cmp_eq_u32 s54, 2
	v_add_f32_e32 v6, v6, v7
	v_add_f32_e32 v167, v167, v6
	s_mov_b64 s[62:63], 0
	s_cbranch_scc0 .LBB0_975
	s_mov_b32 s4, s50
	s_mov_b32 s50, s1
	s_mov_b32 s54, s87
	s_mov_b32 s14, s44
	s_branch .LBB0_946

.LBB0_985:
	v_add_u32_e32 v10, s51, v188
	v_add3_u32 v189, v10, v181, v180
	v_add_u32_e32 v192, v10, v182
	ds_read_b64_tr_b16 v[6:7], v189 offset:8192
	ds_read_b64_tr_b16 v[8:9], v189 offset:9216
	ds_read_b64_tr_b16 v[10:11], v192 offset:8192
	ds_read_b64_tr_b16 v[12:13], v192 offset:9216
	s_nop 2
	v_max_f32_e32 v2, v129, v129
	v_max_f32_e32 v3, v128, v128
	v_max_f32_e32 v2, v3, v2
	v_max3_f32 v3, v130, v131, v113
	v_max3_f32 v2, v2, v112, v114
	v_max3_f32 v2, v2, v115, v132
	v_max3_f32 v3, v3, v134, v135
	v_max3_f32 v2, v2, v133, v116
	v_max3_f32 v3, v3, v118, v119
	v_max3_f32 v2, v2, v117, v136
	v_max3_f32 v3, v3, v138, v139
	v_max3_f32 v2, v2, v137, v120
	v_max3_f32 v3, v3, v122, v123
	v_max3_f32 v2, v2, v121, v140
	v_max3_f32 v3, v3, v142, v143
	v_max3_f32 v2, v2, v141, v124
	v_max3_f32 v3, v3, v126, v127
	v_max3_f32 v2, v2, v125, v3
	v_mov_b32_e32 v3, v2
	s_nop 1
	v_permlane32_swap_b32_e32 v2, v3
	v_max_f32_e32 v3, v3, v3
	v_max_f32_e32 v2, v2, v2
	v_max_f32_e32 v2, v2, v3
	v_cmp_lt_f32_e32 vcc, s91, v2
	s_cbranch_vccz .LBB0_987
	s_nop 0
	v_cndmask_b32_e32 v3, 0, v2, vcc
	v_exp_f32_e64 v2, -v3
	v_sub_f32_e32 v127, v127, v3
	v_sub_f32_e32 v126, v126, v3
	v_sub_f32_e32 v125, v125, v3
	v_sub_f32_e32 v124, v124, v3
	v_sub_f32_e32 v123, v123, v3
	v_sub_f32_e32 v122, v122, v3
	v_sub_f32_e32 v121, v121, v3
	v_sub_f32_e32 v120, v120, v3
	v_sub_f32_e32 v119, v119, v3
	v_sub_f32_e32 v118, v118, v3
	v_sub_f32_e32 v117, v117, v3
	v_sub_f32_e32 v116, v116, v3
	v_sub_f32_e32 v115, v115, v3
	v_sub_f32_e32 v114, v114, v3
	v_sub_f32_e32 v113, v113, v3
	v_sub_f32_e32 v112, v112, v3
	v_sub_f32_e32 v143, v143, v3
	v_sub_f32_e32 v142, v142, v3
	v_sub_f32_e32 v141, v141, v3
	v_sub_f32_e32 v140, v140, v3
	v_sub_f32_e32 v139, v139, v3
	v_sub_f32_e32 v138, v138, v3
	v_sub_f32_e32 v137, v137, v3
	v_sub_f32_e32 v136, v136, v3
	v_sub_f32_e32 v135, v135, v3
	v_sub_f32_e32 v134, v134, v3
	v_sub_f32_e32 v133, v133, v3
	v_sub_f32_e32 v132, v132, v3
	v_sub_f32_e32 v131, v131, v3
	v_sub_f32_e32 v130, v130, v3
	v_sub_f32_e32 v129, v129, v3
	v_sub_f32_e32 v128, v128, v3
	v_add_f32_e32 v0, v0, v3
	v_mul_f32_e32 v166, v166, v2
	v_mul_f32_e32 v110, v110, v2
	v_mul_f32_e32 v111, v111, v2
	v_mul_f32_e32 v108, v108, v2
	v_mul_f32_e32 v109, v109, v2
	v_mul_f32_e32 v106, v106, v2
	v_mul_f32_e32 v107, v107, v2
	v_mul_f32_e32 v104, v104, v2
	v_mul_f32_e32 v105, v105, v2
	v_mul_f32_e32 v102, v102, v2
	v_mul_f32_e32 v103, v103, v2
	v_mul_f32_e32 v100, v100, v2
	v_mul_f32_e32 v101, v101, v2
	v_mul_f32_e32 v98, v98, v2
	v_mul_f32_e32 v99, v99, v2
	v_mul_f32_e32 v96, v96, v2
	v_mul_f32_e32 v97, v97, v2
	v_mul_f32_e32 v94, v94, v2
	v_mul_f32_e32 v95, v95, v2
	v_mul_f32_e32 v92, v92, v2
	v_mul_f32_e32 v93, v93, v2
	v_mul_f32_e32 v90, v90, v2
	v_mul_f32_e32 v91, v91, v2
	v_mul_f32_e32 v88, v88, v2
	v_mul_f32_e32 v89, v89, v2
	v_mul_f32_e32 v86, v86, v2
	v_mul_f32_e32 v87, v87, v2
	v_mul_f32_e32 v84, v84, v2
	v_mul_f32_e32 v85, v85, v2
	v_mul_f32_e32 v82, v82, v2
	v_mul_f32_e32 v83, v83, v2
	v_mul_f32_e32 v80, v80, v2
	v_mul_f32_e32 v81, v81, v2
.LBB0_987:
	v_exp_f32_e32 v14, v128
	v_exp_f32_e32 v15, v129
	v_exp_f32_e32 v130, v130
	v_exp_f32_e32 v131, v131
	v_exp_f32_e32 v132, v132
	v_exp_f32_e32 v133, v133
	v_exp_f32_e32 v134, v134
	v_exp_f32_e32 v135, v135
	v_exp_f32_e32 v128, v112
	v_exp_f32_e32 v129, v113
	v_exp_f32_e32 v190, v114
	v_exp_f32_e32 v191, v115
	ds_read_b64_tr_b16 v[112:113], v189 offset:10240
	ds_read_b64_tr_b16 v[114:115], v189 offset:11264
	v_cvt_pk_bf16_f32 v2, v14, v15
	v_cvt_pk_bf16_f32 v3, v130, v131
	v_cvt_pk_bf16_f32 v4, v132, v133
	v_cvt_pk_bf16_f32 v5, v134, v135
	v_exp_f32_e32 v136, v136
	v_exp_f32_e32 v137, v137
	s_waitcnt lgkmcnt(4)
	v_mfma_f32_32x32x16_bf16 v[96:111], v[6:9], v[2:5], v[96:111]
	v_exp_f32_e32 v138, v138
	v_exp_f32_e32 v139, v139
	v_exp_f32_e32 v140, v140
	v_exp_f32_e32 v141, v141
	ds_read_b64_tr_b16 v[6:7], v192 offset:10240
	ds_read_b64_tr_b16 v[8:9], v192 offset:11264
	v_exp_f32_e32 v142, v142
	v_exp_f32_e32 v143, v143
	s_waitcnt lgkmcnt(4)
	v_mfma_f32_32x32x16_bf16 v[80:95], v[10:13], v[2:5], v[80:95]
	v_cvt_pk_bf16_f32 v2, v136, v137
	v_cvt_pk_bf16_f32 v3, v138, v139
	v_cvt_pk_bf16_f32 v4, v140, v141
	v_cvt_pk_bf16_f32 v5, v142, v143
	v_exp_f32_e32 v116, v116
	v_exp_f32_e32 v117, v117
	v_exp_f32_e32 v118, v118
	s_waitcnt lgkmcnt(2)
	v_mfma_f32_32x32x16_bf16 v[96:111], v[112:115], v[2:5], v[96:111]
	v_exp_f32_e32 v119, v119
	ds_read_b64_tr_b16 v[112:113], v189 offset:12288
	ds_read_b64_tr_b16 v[114:115], v189 offset:13312
	v_cvt_pk_bf16_f32 v10, v128, v129
	v_cvt_pk_bf16_f32 v11, v190, v191
	v_cvt_pk_bf16_f32 v12, v116, v117
	v_cvt_pk_bf16_f32 v13, v118, v119
	v_exp_f32_e32 v124, v124
	s_waitcnt lgkmcnt(2)
	v_mfma_f32_32x32x16_bf16 v[80:95], v[6:9], v[2:5], v[80:95]
	ds_read_b64_tr_b16 v[2:3], v192 offset:12288
	ds_read_b64_tr_b16 v[4:5], v192 offset:13312
	ds_read_b64_tr_b16 v[6:7], v189 offset:14336
	ds_read_b64_tr_b16 v[8:9], v189 offset:15360
	v_exp_f32_e32 v125, v125
	v_exp_f32_e32 v120, v120
	v_exp_f32_e32 v121, v121
	v_exp_f32_e32 v122, v122
	v_exp_f32_e32 v123, v123
	v_exp_f32_e32 v126, v126
	s_waitcnt lgkmcnt(4)
	v_mfma_f32_32x32x16_bf16 v[96:111], v[112:115], v[10:13], v[96:111]
	v_exp_f32_e32 v127, v127
	ds_read_b64_tr_b16 v[112:113], v192 offset:14336
	ds_read_b64_tr_b16 v[114:115], v192 offset:15360
	v_add_f32_e32 v14, v128, v14
	v_add_f32_e32 v15, v129, v15
	v_add_f32_e32 v128, v124, v140
	v_add_f32_e32 v129, v125, v141
	v_add_f32_e32 v138, v122, v138
	v_add_f32_e32 v139, v123, v139
	v_add_f32_e32 v130, v190, v130
	v_add_f32_e32 v131, v191, v131
	v_add_f32_e32 v142, v126, v142
	v_add_f32_e32 v143, v127, v143
	s_waitcnt lgkmcnt(4)
	v_mfma_f32_32x32x16_bf16 v[80:95], v[2:5], v[10:13], v[80:95]
	v_add_f32_e64 v2, v116, v132
	v_add_f32_e64 v3, v117, v133
	v_cvt_pk_bf16_f32 v4, v124, v125
	v_add_f32_e64 v10, v2, v128
	v_add_f32_e64 v11, v3, v129
	v_cvt_pk_bf16_f32 v2, v120, v121
	v_cvt_pk_bf16_f32 v3, v122, v123
	v_cvt_pk_bf16_f32 v5, v126, v127
	v_add_f32_e32 v118, v118, v134
	v_add_f32_e32 v119, v119, v135
	v_add_f32_e32 v134, v120, v136
	v_add_f32_e32 v135, v121, v137
	s_waitcnt lgkmcnt(2)
	v_mfma_f32_32x32x16_bf16 v[96:111], v[6:9], v[2:5], v[96:111]
	v_add_f32_e64 v12, v14, v134
	v_add_f32_e64 v13, v15, v135
	v_add_f32_e64 v6, v118, v142
	v_add_f32_e64 v7, v119, v143
	v_add_f32_e64 v8, v130, v138
	v_add_f32_e64 v9, v131, v139
	s_and_b32 s0, s13, s0
	v_add_f32_e32 v6, v8, v6
	v_add_f32_e32 v7, v9, v7
	v_add_f32_e32 v8, v12, v10
	v_add_f32_e32 v9, v13, v11
	s_waitcnt vmcnt(2) lgkmcnt(0)
	s_waitcnt lgkmcnt(0)
	v_mfma_f32_32x32x16_bf16 v[80:95], v[112:115], v[2:5], v[80:95]
	v_add_f32_e64 v6, v8, v6
	v_add_f32_e64 v7, v9, v7
	s_barrier
	s_and_b64 s[4:5], s[6:7], exec
	v_add_f32_e32 v6, v6, v7
	s_cselect_b32 s4, -1, s1
	v_add_f32_e32 v166, v166, v6
	s_cmp_gt_i32 s11, -1
	s_cbranch_scc0 .LBB0_884
	s_mov_b32 s1, s51
	s_mov_b32 s51, s12
	s_mov_b32 s97, s11
	s_branch .LBB0_981
